# v52 + attention MODE-1 epilogue: xor-16 hop of the rmsnorm butterfly via v_mov + v_permlane16_swap + add (no LDS round trips left in that reduction)
# baseline (speedup 1.0000x reference)
.LBB0_749:
	s_or_b64 exec, exec, s[4:5]
	s_waitcnt lgkmcnt(0)
	ds_read_b128 v[68:71], v66 offset:128
	ds_read_b128 v[72:75], v66 offset:160
	s_mov_b64 s[6:7], s[0:1]
	s_add_u32 s4, s10, s13
	s_addc_u32 s5, s37, s14
	s_waitcnt lgkmcnt(1)
	v_rcp_f32_e32 v67, v68
	v_rcp_f32_e32 v76, v69
	v_rcp_f32_e32 v77, v70
	v_rcp_f32_e32 v78, v71
	s_waitcnt lgkmcnt(0)
	v_rcp_f32_e32 v79, v72
	ds_read_b128 v[68:71], v66 offset:192
	v_rcp_f32_e32 v80, v73
	v_rcp_f32_e32 v81, v74
	v_rcp_f32_e32 v82, v75
	ds_read_b128 v[72:75], v66 offset:224
	s_load_dwordx2 s[6:7], s[6:7], 0xa0
	s_lshl_b64 s[4:5], s[4:5], 11
	s_waitcnt lgkmcnt(0)
	v_rcp_f32_e32 v66, v68
	v_rcp_f32_e32 v68, v69
	v_rcp_f32_e32 v69, v70
	s_add_u32 s8, s6, s4
	v_rcp_f32_e32 v70, v71
	v_rcp_f32_e32 v71, v72
	v_rcp_f32_e32 v72, v73
	v_rcp_f32_e32 v73, v74
	v_rcp_f32_e32 v74, v75
	s_addc_u32 s9, s7, s5
	s_lshl_b32 s4, s12, 12
	s_add_i32 s10, s4, 0
	v_mul_f32_e32 v18, v18, v67
	v_mul_f32_e32 v50, v50, v67
	v_mul_f32_e32 v34, v34, v67
	v_mul_f32_e32 v67, v2, v67
	s_add_i32 s10, s10, 0x16800
	v_lshlrev_b32_e32 v2, 4, v1
	v_mul_f32_e32 v75, v3, v76
	s_mov_b64 s[4:5], s[0:1]
	v_and_b32_e32 v3, 0x380, v2
	v_add_u32_e32 v2, s10, v188
	v_mul_f32_e32 v89, v48, v73
	v_mul_f32_e32 v48, v65, v74
	v_add_u32_e32 v65, v2, v3
	v_mul_f32_e32 v19, v19, v76
	v_mul_f32_e32 v51, v51, v76
	v_mul_f32_e32 v35, v35, v76
	v_mul_f32_e32 v76, v4, v77
	s_load_dwordx2 s[4:5], s[4:5], 0x70
	v_lshlrev_b32_e32 v3, 1, v207
	v_lshlrev_b32_e32 v4, 9, v208
	s_waitcnt vmcnt(5)
	ds_write_b128 v65, v[138:141]
	ds_write_b128 v65, v[130:133] offset:1024
	ds_write_b128 v65, v[134:137] offset:2048
	s_waitcnt vmcnt(3)
	ds_write_b128 v65, v[142:145] offset:3072
	v_mul_f32_e32 v85, v10, v66
	v_mul_f32_e32 v10, v27, v68
	v_mul_f32_e32 v27, v59, v68
	v_mul_f32_e32 v59, v60, v69
	v_mul_f32_e32 v60, v12, v69
	v_mul_f32_e32 v12, v29, v70
	v_mul_f32_e32 v29, v61, v70
	v_mul_f32_e32 v30, v30, v71
	v_mul_f32_e32 v61, v62, v71
	v_mul_f32_e32 v86, v46, v71
	v_mul_f32_e32 v87, v14, v71
	v_add3_u32 v71, s10, v3, v4
	s_waitcnt lgkmcnt(0)
	v_mul_f32_e32 v20, v20, v77
	v_mul_f32_e32 v52, v52, v77
	v_mul_f32_e32 v36, v36, v77
	v_mul_f32_e32 v21, v21, v78
	v_mul_f32_e32 v53, v53, v78
	v_mul_f32_e32 v77, v37, v78
	v_mul_f32_e32 v78, v5, v78
	v_mul_f32_e32 v5, v22, v79
	v_mul_f32_e32 v22, v54, v79
	v_mul_f32_e32 v38, v38, v79
	v_mul_f32_e32 v79, v6, v79
	v_mul_f32_e32 v6, v23, v80
	v_mul_f32_e32 v23, v55, v80
	v_mul_f32_e32 v83, v39, v80
	v_mul_f32_e32 v80, v7, v80
	v_mul_f32_e32 v7, v24, v81
	v_mul_f32_e32 v24, v56, v81
	v_mul_f32_e32 v84, v40, v81
	v_mul_f32_e32 v81, v8, v81
	v_mul_f32_e32 v8, v25, v82
	v_mul_f32_e32 v25, v57, v82
	v_mul_f32_e32 v41, v41, v82
	v_mul_f32_e32 v57, v9, v82
	v_mul_f32_e32 v9, v26, v66
	v_mul_f32_e32 v26, v58, v66
	v_mul_f32_e32 v82, v42, v66
	v_mul_f32_e32 v28, v28, v69
	v_mul_f32_e32 v44, v44, v69
	v_mul_f32_e32 v66, v31, v72
	v_mul_f32_e32 v69, v32, v73
	v_mul_f32_e32 v90, v16, v73
	v_mul_f32_e32 v16, v33, v74
	ds_read_u16 v14, v71
	ds_read_u16 v31, v71 offset:64
	ds_read_u16 v32, v71 offset:128
	ds_read_u16 v33, v71 offset:192
	ds_read_u16 v37, v71 offset:256
	ds_read_u16 v39, v71 offset:320
	ds_read_u16 v40, v71 offset:384
	ds_read_u16 v42, v71 offset:448
	s_waitcnt lgkmcnt(0)
	v_lshlrev_b32_e32 v14, 16, v14
	v_fma_f32 v92, -v203, v18, v14
	v_lshlrev_b32_e32 v14, 16, v31
	v_fma_f32 v93, -v203, v50, v14
	v_lshlrev_b32_e32 v14, 16, v32
	v_fma_f32 v94, -v203, v19, v14
	v_lshlrev_b32_e32 v14, 16, v33
	v_fma_f32 v51, -v203, v51, v14
	v_lshlrev_b32_e32 v14, 16, v37
	v_fma_f32 v37, -v203, v20, v14
	v_lshlrev_b32_e32 v14, 16, v39
	v_fma_f32 v32, -v203, v52, v14
	v_lshlrev_b32_e32 v14, 16, v40
	v_fma_f32 v46, -v203, v21, v14
	v_lshlrev_b32_e32 v14, 16, v42
	v_fma_f32 v40, -v203, v53, v14
	ds_read_u16 v14, v71 offset:1024
	ds_read_u16 v18, v71 offset:1088
	ds_read_u16 v19, v71 offset:1152
	ds_read_u16 v20, v71 offset:1216
	ds_read_u16 v21, v71 offset:1280
	ds_read_u16 v31, v71 offset:1344
	ds_read_u16 v33, v71 offset:1408
	ds_read_u16 v39, v71 offset:1472
	s_waitcnt lgkmcnt(7)
	v_lshlrev_b32_e32 v14, 16, v14
	v_fma_f32 v55, -v203, v5, v14
	s_waitcnt lgkmcnt(6)
	v_lshlrev_b32_e32 v5, 16, v18
	v_mul_f32_e32 v91, v49, v74
	v_fma_f32 v49, -v203, v22, v5
	s_waitcnt lgkmcnt(5)
	v_lshlrev_b32_e32 v5, 16, v19
	v_mul_f32_e32 v43, v43, v68
	v_mul_f32_e32 v11, v11, v68
	v_mul_f32_e32 v68, v63, v72
	v_fma_f32 v63, -v203, v6, v5
	s_waitcnt lgkmcnt(4)
	v_lshlrev_b32_e32 v5, 16, v20
	v_fma_f32 v58, -v203, v23, v5
	s_waitcnt lgkmcnt(3)
	v_lshlrev_b32_e32 v5, 16, v21
	v_mul_f32_e32 v45, v45, v70
	v_mul_f32_e32 v13, v13, v70
	v_mul_f32_e32 v70, v64, v73
	v_fma_f32 v64, -v203, v7, v5
	s_waitcnt lgkmcnt(2)
	v_lshlrev_b32_e32 v5, 16, v31
	v_fma_f32 v62, -v203, v24, v5
	s_waitcnt lgkmcnt(1)
	v_lshlrev_b32_e32 v5, 16, v33
	v_fma_f32 v56, -v203, v8, v5
	s_waitcnt lgkmcnt(0)
	v_lshlrev_b32_e32 v5, 16, v39
	v_fma_f32 v54, -v203, v25, v5
	ds_read_u16 v5, v71 offset:2048
	ds_read_u16 v6, v71 offset:2112
	ds_read_u16 v7, v71 offset:2176
	ds_read_u16 v8, v71 offset:2240
	ds_read_u16 v14, v71 offset:2304
	ds_read_u16 v18, v71 offset:2368
	ds_read_u16 v19, v71 offset:2432
	ds_read_u16 v20, v71 offset:2496
	s_waitcnt lgkmcnt(7)
	v_lshlrev_b32_e32 v5, 16, v5
	v_fma_f32 v50, -v203, v9, v5
	s_waitcnt lgkmcnt(6)
	v_lshlrev_b32_e32 v5, 16, v6
	v_mul_f32_e32 v88, v47, v72
	v_fma_f32 v47, -v203, v26, v5
	s_waitcnt lgkmcnt(5)
	v_lshlrev_b32_e32 v5, 16, v7
	v_fma_f32 v42, -v203, v10, v5
	s_waitcnt lgkmcnt(4)
	v_lshlrev_b32_e32 v5, 16, v8
	v_fma_f32 v39, -v203, v27, v5
	s_waitcnt lgkmcnt(3)
	v_lshlrev_b32_e32 v5, 16, v14
	v_fma_f32 v33, -v203, v28, v5
	s_waitcnt lgkmcnt(2)
	v_lshlrev_b32_e32 v5, 16, v18
	v_fma_f32 v31, -v203, v59, v5
	s_waitcnt lgkmcnt(1)
	v_lshlrev_b32_e32 v5, 16, v19
	v_fma_f32 v23, -v203, v12, v5
	s_waitcnt lgkmcnt(0)
	v_lshlrev_b32_e32 v5, 16, v20
	v_fma_f32 v21, -v203, v29, v5
	ds_read_u16 v5, v71 offset:3072
	ds_read_u16 v6, v71 offset:3136
	ds_read_u16 v7, v71 offset:3200
	ds_read_u16 v8, v71 offset:3264
	ds_read_u16 v18, v71 offset:3328
	ds_read_u16 v19, v71 offset:3392
	ds_read_u16 v20, v71 offset:3456
	ds_read_u16 v22, v71 offset:3520
	s_waitcnt lgkmcnt(7)
	v_lshlrev_b32_e32 v5, 16, v5
	v_fma_f32 v14, -v203, v30, v5
	s_waitcnt lgkmcnt(6)
	v_lshlrev_b32_e32 v5, 16, v6
	v_fma_f32 v12, -v203, v61, v5
	s_waitcnt lgkmcnt(5)
	v_lshlrev_b32_e32 v5, 16, v7
	v_fma_f32 v9, -v203, v66, v5
	s_waitcnt lgkmcnt(4)
	v_lshlrev_b32_e32 v5, 16, v8
	v_fma_f32 v10, -v203, v68, v5
	s_waitcnt lgkmcnt(3)
	v_lshlrev_b32_e32 v5, 16, v18
	v_fma_f32 v8, -v203, v69, v5
	s_waitcnt lgkmcnt(2)
	v_lshlrev_b32_e32 v5, 16, v19
	s_waitcnt lgkmcnt(0)
	ds_write_b128 v65, v[114:117]
	s_waitcnt vmcnt(2)
	ds_write_b128 v65, v[118:121] offset:1024
	s_waitcnt vmcnt(1)
	ds_write_b128 v65, v[122:125] offset:2048
	s_waitcnt vmcnt(0)
	ds_write_b128 v65, v[126:129] offset:3072
	v_fma_f32 v7, -v203, v70, v5
	s_waitcnt lgkmcnt(5)
	v_lshlrev_b32_e32 v5, 16, v20
	s_waitcnt lgkmcnt(0)
	v_fma_f32 v5, -v203, v16, v5
	s_waitcnt lgkmcnt(4)
	v_lshlrev_b32_e32 v6, 16, v22
	ds_read_u16 v16, v71
	ds_read_u16 v18, v71 offset:64
	ds_read_u16 v19, v71 offset:128
	ds_read_u16 v20, v71 offset:192
	ds_read_u16 v22, v71 offset:256
	ds_read_u16 v24, v71 offset:320
	ds_read_u16 v25, v71 offset:384
	ds_read_u16 v26, v71 offset:448
	s_waitcnt lgkmcnt(7)
	v_lshlrev_b32_e32 v16, 16, v16
	v_fma_f32 v29, -v203, v34, v16
	s_waitcnt lgkmcnt(6)
	v_lshlrev_b32_e32 v16, 16, v18
	v_fma_f32 v52, -v203, v67, v16
	s_waitcnt lgkmcnt(5)
	v_lshlrev_b32_e32 v16, 16, v19
	v_fma_f32 v59, -v203, v35, v16
	s_waitcnt lgkmcnt(4)
	v_lshlrev_b32_e32 v16, 16, v20
	v_fma_f32 v6, -v203, v48, v6
	v_fma_f32 v67, -v203, v75, v16
	ds_read_u16 v16, v71 offset:1024
	ds_read_u16 v18, v71 offset:1088
	ds_read_u16 v19, v71 offset:1152
	ds_read_u16 v20, v71 offset:1216
	ds_read_u16 v27, v71 offset:1280
	ds_read_u16 v28, v71 offset:1344
	ds_read_u16 v30, v71 offset:1408
	ds_read_u16 v34, v71 offset:1472
	ds_read_u16 v35, v71 offset:2048
	ds_read_u16 v48, v71 offset:2112
	ds_read_u16 v53, v71 offset:2176
	ds_read_u16 v75, v71 offset:2240
	ds_read_u16 v95, v71 offset:2304
	ds_read_u16 v96, v71 offset:2368
	ds_read_u16 v97, v71 offset:2432
	ds_read_u16 v98, v71 offset:2496
	ds_read_u16 v99, v71 offset:3072
	ds_read_u16 v100, v71 offset:3136
	ds_read_u16 v101, v71 offset:3200
	ds_read_u16 v102, v71 offset:3264
	ds_read_u16 v103, v71 offset:3328
	ds_read_u16 v104, v71 offset:3392
	ds_read_u16 v105, v71 offset:3456
	ds_read_u16 v106, v71 offset:3520
	s_waitcnt lgkmcnt(14)
	v_lshlrev_b32_e32 v22, 16, v22
	v_fma_f32 v109, -v203, v36, v22
	v_lshlrev_b32_e32 v22, 16, v24
	v_lshlrev_b32_e32 v16, 16, v16
	v_fma_f32 v76, -v203, v76, v22
	v_lshlrev_b32_e32 v22, 16, v25
	v_fma_f32 v110, -v203, v38, v16
	v_lshlrev_b32_e32 v16, 16, v18
	s_waitcnt lgkmcnt(0)
	v_lshlrev_b32_e32 v61, 2, v207
	v_fma_f32 v77, -v203, v77, v22
	v_lshlrev_b32_e32 v22, 16, v26
	v_fma_f32 v66, -v203, v79, v16
	v_lshlrev_b32_e32 v16, 16, v19
	global_load_dword v107, v61, s[4:5]
	global_load_dword v108, v61, s[4:5] offset:128
	v_fma_f32 v78, -v203, v78, v22
	v_fma_f32 v71, -v203, v83, v16
	v_lshlrev_b32_e32 v16, 16, v20
	global_load_dword v20, v61, s[4:5] offset:256
	global_load_dword v22, v61, s[4:5] offset:384
	v_fma_f32 v70, -v203, v80, v16
	v_lshlrev_b32_e32 v16, 16, v27
	v_mul_f32_e32 v17, v17, v74
	v_fma_f32 v74, -v203, v84, v16
	v_lshlrev_b32_e32 v16, 16, v28
	v_fma_f32 v73, -v203, v81, v16
	v_lshlrev_b32_e32 v16, 16, v30
	v_mul_f32_e32 v15, v15, v72
	v_fma_f32 v72, -v203, v41, v16
	v_lshlrev_b32_e32 v16, 16, v34
	v_fma_f32 v69, -v203, v57, v16
	v_lshlrev_b32_e32 v16, 16, v35
	v_fma_f32 v68, -v203, v82, v16
	v_lshlrev_b32_e32 v16, 16, v48
	v_fma_f32 v65, -v203, v85, v16
	s_waitcnt lgkmcnt(13)
	v_lshlrev_b32_e32 v16, 16, v53
	v_fma_f32 v61, -v203, v43, v16
	s_waitcnt lgkmcnt(12)
	v_lshlrev_b32_e32 v16, 16, v75
	v_fma_f32 v57, -v203, v11, v16
	v_mul_f32_e32 v16, v93, v93
	v_mul_f32_e32 v18, v52, v52
	v_fmac_f32_e32 v16, v92, v92
	v_fmac_f32_e32 v18, v29, v29
	v_add_f32_e32 v16, v16, v18
	s_waitcnt lgkmcnt(12)
	v_lshlrev_b32_e32 v11, 16, v95
	v_fma_f32 v53, -v203, v44, v11
	s_waitcnt lgkmcnt(11)
	v_lshlrev_b32_e32 v11, 16, v96
	v_fma_f32 v48, -v203, v60, v11
	s_waitcnt lgkmcnt(0)
	v_add_f32_dpp v16, v16, v16 quad_perm:[1,0,3,2] row_mask:0xf bank_mask:0xf
	v_lshlrev_b32_e32 v11, 16, v97
	v_fma_f32 v45, -v203, v45, v11
	v_lshlrev_b32_e32 v11, 16, v98
	v_fma_f32 v41, -v203, v13, v11
	s_waitcnt lgkmcnt(0)
	v_add_f32_dpp v13, v16, v16 quad_perm:[2,3,0,1] row_mask:0xf bank_mask:0xf
	v_lshlrev_b32_e32 v11, 16, v99
	v_fma_f32 v38, -v203, v86, v11
	v_lshlrev_b32_e32 v11, 16, v100
	v_fma_f32 v34, -v203, v87, v11
	v_add_f32_dpp v13, v13, v13 row_half_mirror row_mask:0xf bank_mask:0xf
	v_lshlrev_b32_e32 v11, 16, v101
	v_fma_f32 v30, -v203, v88, v11
	v_lshlrev_b32_e32 v11, 16, v102
	v_fma_f32 v24, -v203, v15, v11
	v_add_f32_dpp v15, v13, v13 row_mirror row_mask:0xf bank_mask:0xf
	v_mov_b32_e32 v18, v15
	v_lshlrev_b32_e32 v11, 16, v103
	v_fma_f32 v16, -v203, v89, v11
	v_lshlrev_b32_e32 v11, 16, v104
	v_fma_f32 v19, -v203, v90, v11
	s_waitcnt lgkmcnt(0)
	v_permlane16_swap_b32_e32 v15, v18
	v_add_f32_e32 v15, v15, v18
	v_fmamk_f32 v15, v15, 0x3c000000, v204
	v_rsq_f32_e32 v224, v15
	v_lshlrev_b32_e32 v11, 16, v105
	v_fma_f32 v13, -v203, v91, v11
	v_lshlrev_b32_e32 v11, 16, v106
	v_fma_f32 v15, -v203, v17, v11
	v_lshrrev_b32_e32 v1, 3, v1
	v_mov_b32_e32 v189, v146
	s_waitcnt vmcnt(3)
	v_mul_f32_e32 v18, 0x3f24fd5c, v107
	v_mul_f32_e32 v26, v51, v51
	v_mul_f32_e32 v27, v67, v67
	v_fmac_f32_e32 v26, v94, v94
	v_fmac_f32_e32 v27, v59, v59
	v_add_f32_e32 v26, v26, v27
	s_waitcnt vmcnt(2)
	v_mul_f32_e32 v17, 0x3f24fd5c, v108
	s_nop 0
	v_add_f32_dpp v27, v26, v26 quad_perm:[1,0,3,2] row_mask:0xf bank_mask:0xf
	s_waitcnt vmcnt(1)
	v_mul_f32_e32 v26, 0x3f24fd5c, v20
	s_waitcnt vmcnt(0)
	v_mul_f32_e32 v25, 0x3f24fd5c, v22
	v_add_f32_dpp v20, v27, v27 quad_perm:[2,3,0,1] row_mask:0xf bank_mask:0xf
	s_nop 1
	v_add_f32_dpp v20, v20, v20 row_half_mirror row_mask:0xf bank_mask:0xf
	v_mov_b32_e32 v35, v224
	s_nop 0
	v_add_f32_dpp v20, v20, v20 row_mirror row_mask:0xf bank_mask:0xf
	v_mov_b32_e32 v22, v20
	v_mul_f32_e32 v11, v18, v35
	v_mul_f32_e32 v27, v92, v11
	v_mul_f32_e32 v11, v17, v35
	v_mul_f32_e32 v28, v93, v11
	s_waitcnt lgkmcnt(0)
	v_permlane16_swap_b32_e32 v20, v22
	v_add_f32_e32 v20, v20, v22
	v_fmamk_f32 v20, v20, 0x3c000000, v204
	v_rsq_f32_e32 v225, v20
	v_mul_f32_e32 v11, v26, v35
	v_mul_f32_e32 v11, v29, v11
	v_mul_f32_e32 v29, v32, v32
	v_mul_f32_e32 v36, v76, v76
	v_fmac_f32_e32 v29, v37, v37
	v_fmac_f32_e32 v36, v109, v109
	v_add_f32_e32 v29, v29, v36
	s_nop 1
	v_add_f32_dpp v29, v29, v29 quad_perm:[1,0,3,2] row_mask:0xf bank_mask:0xf
	v_mul_f32_e32 v20, v25, v35
	v_mul_f32_e32 v20, v52, v20
	v_add_f32_dpp v29, v29, v29 quad_perm:[2,3,0,1] row_mask:0xf bank_mask:0xf
	s_nop 1
	v_add_f32_dpp v29, v29, v29 row_half_mirror row_mask:0xf bank_mask:0xf
	v_mov_b32_e32 v44, v225
	s_nop 0
	v_add_f32_dpp v29, v29, v29 row_mirror row_mask:0xf bank_mask:0xf
	v_mov_b32_e32 v43, v29
	v_mul_f32_e32 v22, v18, v44
	v_mul_f32_e32 v35, v94, v22
	v_mul_f32_e32 v22, v17, v44
	s_waitcnt lgkmcnt(0)
	v_permlane16_swap_b32_e32 v29, v43
	v_add_f32_e32 v29, v29, v43
	v_fmamk_f32 v29, v29, 0x3c000000, v204
	v_rsq_f32_e32 v226, v29
	v_mul_f32_e32 v36, v51, v22
	v_mul_f32_e32 v22, v26, v44
	v_mul_f32_e32 v22, v59, v22
	v_mul_f32_e32 v51, v40, v40
	v_mul_f32_e32 v52, v78, v78
	v_fmac_f32_e32 v51, v46, v46
	v_fmac_f32_e32 v52, v77, v77
	v_add_f32_e32 v51, v51, v52
	s_nop 1
	v_add_f32_dpp v51, v51, v51 quad_perm:[1,0,3,2] row_mask:0xf bank_mask:0xf
	v_mul_f32_e32 v29, v25, v44
	v_mul_f32_e32 v29, v67, v29
	v_add_f32_dpp v44, v51, v51 quad_perm:[2,3,0,1] row_mask:0xf bank_mask:0xf
	s_nop 1
	v_add_f32_dpp v44, v44, v44 row_half_mirror row_mask:0xf bank_mask:0xf
	v_mov_b32_e32 v52, v226
	s_nop 0
	v_add_f32_dpp v44, v44, v44 row_mirror row_mask:0xf bank_mask:0xf
	v_mov_b32_e32 v51, v44
	v_mul_f32_e32 v43, v18, v52
	v_mul_f32_e32 v43, v37, v43
	v_mul_f32_e32 v37, v17, v52
	s_waitcnt lgkmcnt(0)
	v_permlane16_swap_b32_e32 v44, v51
	v_add_f32_e32 v44, v44, v51
	v_fmamk_f32 v44, v44, 0x3c000000, v204
	v_rsq_f32_e32 v227, v44
	v_mul_f32_e32 v44, v32, v37
	v_mul_f32_e32 v32, v26, v52
	v_mul_f32_e32 v32, v109, v32
	v_mul_f32_e32 v59, v49, v49
	v_mul_f32_e32 v60, v66, v66
	v_fmac_f32_e32 v59, v55, v55
	v_fmac_f32_e32 v60, v110, v110
	v_add_f32_e32 v59, v59, v60
	s_nop 1
	v_add_f32_dpp v59, v59, v59 quad_perm:[1,0,3,2] row_mask:0xf bank_mask:0xf
	v_mul_f32_e32 v37, v25, v52
	v_mul_f32_e32 v37, v76, v37
	v_add_f32_dpp v52, v59, v59 quad_perm:[2,3,0,1] row_mask:0xf bank_mask:0xf
	s_nop 1
	v_add_f32_dpp v52, v52, v52 row_half_mirror row_mask:0xf bank_mask:0xf
	v_mov_b32_e32 v60, v227
	s_nop 0
	v_add_f32_dpp v52, v52, v52 row_mirror row_mask:0xf bank_mask:0xf
	v_mov_b32_e32 v59, v52
	v_mul_f32_e32 v51, v18, v60
	v_mul_f32_e32 v51, v46, v51
	v_mul_f32_e32 v46, v17, v60
	s_waitcnt lgkmcnt(0)
	v_permlane16_swap_b32_e32 v52, v59
	v_add_f32_e32 v52, v52, v59
	v_fmamk_f32 v52, v52, 0x3c000000, v204
	v_rsq_f32_e32 v228, v52
	v_mul_f32_e32 v52, v40, v46
	v_mul_f32_e32 v40, v26, v60
	v_mul_f32_e32 v40, v77, v40
	v_mul_f32_e32 v67, v58, v58
	v_mul_f32_e32 v75, v70, v70
	v_fmac_f32_e32 v67, v63, v63
	v_fmac_f32_e32 v75, v71, v71
	v_add_f32_e32 v67, v67, v75
	s_nop 1
	v_add_f32_dpp v67, v67, v67 quad_perm:[1,0,3,2] row_mask:0xf bank_mask:0xf
	v_mul_f32_e32 v46, v25, v60
	v_mul_f32_e32 v46, v78, v46
	v_add_f32_dpp v60, v67, v67 quad_perm:[2,3,0,1] row_mask:0xf bank_mask:0xf
	s_nop 1
	v_add_f32_dpp v60, v60, v60 row_half_mirror row_mask:0xf bank_mask:0xf
	v_mov_b32_e32 v75, v228
	s_nop 0
	v_add_f32_dpp v60, v60, v60 row_mirror row_mask:0xf bank_mask:0xf
	v_mov_b32_e32 v67, v60
	v_mul_f32_e32 v59, v18, v75
	v_mul_f32_e32 v59, v55, v59
	v_mul_f32_e32 v55, v17, v75
	s_waitcnt lgkmcnt(0)
	v_permlane16_swap_b32_e32 v60, v67
	v_add_f32_e32 v60, v60, v67
	v_fmamk_f32 v60, v60, 0x3c000000, v204
	v_rsq_f32_e32 v229, v60
	v_mul_f32_e32 v60, v49, v55
	v_mul_f32_e32 v49, v26, v75
	v_mul_f32_e32 v49, v110, v49
	v_mul_f32_e32 v76, v62, v62
	v_mul_f32_e32 v77, v73, v73
	v_fmac_f32_e32 v76, v64, v64
	v_fmac_f32_e32 v77, v74, v74
	v_add_f32_e32 v76, v76, v77
	s_nop 1
	v_add_f32_dpp v76, v76, v76 quad_perm:[1,0,3,2] row_mask:0xf bank_mask:0xf
	v_mul_f32_e32 v55, v25, v75
	v_mul_f32_e32 v55, v66, v55
	v_add_f32_dpp v66, v76, v76 quad_perm:[2,3,0,1] row_mask:0xf bank_mask:0xf
	s_nop 1
	v_add_f32_dpp v66, v66, v66 row_half_mirror row_mask:0xf bank_mask:0xf
	v_mov_b32_e32 v76, v229
	s_nop 0
	v_add_f32_dpp v75, v66, v66 row_mirror row_mask:0xf bank_mask:0xf
	v_mov_b32_e32 v77, v75
	v_mul_f32_e32 v66, v18, v76
	v_mul_f32_e32 v66, v63, v66
	v_mul_f32_e32 v63, v17, v76
	s_waitcnt lgkmcnt(0)
	v_permlane16_swap_b32_e32 v75, v77
	v_add_f32_e32 v67, v75, v77
	v_fmamk_f32 v67, v67, 0x3c000000, v204
	v_rsq_f32_e32 v230, v67
	v_mul_f32_e32 v67, v58, v63
	v_mul_f32_e32 v58, v26, v76
	v_mul_f32_e32 v58, v71, v58
	v_mul_f32_e32 v77, v69, v69
	v_fmac_f32_e32 v77, v72, v72
	v_mul_f32_e32 v71, v54, v54
	v_fmac_f32_e32 v71, v56, v56
	v_add_f32_e32 v71, v71, v77
	s_nop 1
	v_add_f32_dpp v71, v71, v71 quad_perm:[1,0,3,2] row_mask:0xf bank_mask:0xf
	v_mul_f32_e32 v63, v25, v76
	v_mul_f32_e32 v63, v70, v63
	v_add_f32_dpp v70, v71, v71 quad_perm:[2,3,0,1] row_mask:0xf bank_mask:0xf
	s_nop 1
	v_add_f32_dpp v70, v70, v70 row_half_mirror row_mask:0xf bank_mask:0xf
	v_mov_b32_e32 v75, v230
	s_nop 0
	v_add_f32_dpp v71, v70, v70 row_mirror row_mask:0xf bank_mask:0xf
	v_mov_b32_e32 v77, v71
	v_mul_f32_e32 v70, v18, v75
	v_mul_f32_e32 v70, v64, v70
	v_mul_f32_e32 v64, v17, v75
	s_waitcnt lgkmcnt(0)
	v_permlane16_swap_b32_e32 v71, v77
	v_add_f32_e32 v71, v71, v77
	v_fmamk_f32 v71, v71, 0x3c000000, v204
	v_rsq_f32_e32 v231, v71
	v_mul_f32_e32 v71, v62, v64
	v_mul_f32_e32 v62, v26, v75
	v_mul_f32_e32 v62, v74, v62
	v_mul_f32_e32 v77, v65, v65
	v_fmac_f32_e32 v77, v68, v68
	v_mul_f32_e32 v74, v47, v47
	v_fmac_f32_e32 v74, v50, v50
	v_add_f32_e32 v74, v74, v77
	s_nop 1
	v_add_f32_dpp v74, v74, v74 quad_perm:[1,0,3,2] row_mask:0xf bank_mask:0xf
	v_mul_f32_e32 v64, v25, v75
	v_mul_f32_e32 v64, v73, v64
	v_add_f32_dpp v73, v74, v74 quad_perm:[2,3,0,1] row_mask:0xf bank_mask:0xf
	s_nop 1
	v_add_f32_dpp v73, v73, v73 row_half_mirror row_mask:0xf bank_mask:0xf
	v_mov_b32_e32 v75, v231
	s_nop 0
	v_add_f32_dpp v74, v73, v73 row_mirror row_mask:0xf bank_mask:0xf
	v_mov_b32_e32 v77, v74
	v_mul_f32_e32 v73, v18, v75
	v_mul_f32_e32 v73, v56, v73
	v_mul_f32_e32 v56, v17, v75
	s_waitcnt lgkmcnt(0)
	v_permlane16_swap_b32_e32 v74, v77
	v_add_f32_e32 v74, v74, v77
	v_fmamk_f32 v74, v74, 0x3c000000, v204
	v_rsq_f32_e32 v224, v74
	v_mul_f32_e32 v74, v54, v56
	v_mul_f32_e32 v54, v26, v75
	v_mul_f32_e32 v54, v72, v54
	v_mul_f32_e32 v77, v57, v57
	v_fmac_f32_e32 v77, v61, v61
	v_mul_f32_e32 v72, v39, v39
	v_fmac_f32_e32 v72, v42, v42
	v_add_f32_e32 v72, v72, v77
	s_nop 1
	v_add_f32_dpp v72, v72, v72 quad_perm:[1,0,3,2] row_mask:0xf bank_mask:0xf
	v_mul_f32_e32 v56, v25, v75
	v_mul_f32_e32 v56, v69, v56
	v_add_f32_dpp v69, v72, v72 quad_perm:[2,3,0,1] row_mask:0xf bank_mask:0xf
	s_nop 1
	v_add_f32_dpp v69, v69, v69 row_half_mirror row_mask:0xf bank_mask:0xf
	v_mov_b32_e32 v75, v224
	s_nop 0
	v_add_f32_dpp v72, v69, v69 row_mirror row_mask:0xf bank_mask:0xf
	v_mov_b32_e32 v77, v72
	v_mul_f32_e32 v69, v18, v75
	v_mul_f32_e32 v69, v50, v69
	v_mul_f32_e32 v50, v17, v75
	s_waitcnt lgkmcnt(0)
	v_permlane16_swap_b32_e32 v72, v77
	v_add_f32_e32 v72, v72, v77
	v_fmamk_f32 v72, v72, 0x3c000000, v204
	v_rsq_f32_e32 v225, v72
	v_mul_f32_e32 v72, v47, v50
	v_mul_f32_e32 v47, v26, v75
	v_mul_f32_e32 v47, v68, v47
	v_mul_f32_e32 v77, v48, v48
	v_fmac_f32_e32 v77, v53, v53
	v_mul_f32_e32 v68, v31, v31
	v_fmac_f32_e32 v68, v33, v33
	v_add_f32_e32 v68, v68, v77
	s_nop 1
	v_add_f32_dpp v68, v68, v68 quad_perm:[1,0,3,2] row_mask:0xf bank_mask:0xf
	v_mul_f32_e32 v50, v25, v75
	v_mul_f32_e32 v50, v65, v50
	v_add_f32_dpp v65, v68, v68 quad_perm:[2,3,0,1] row_mask:0xf bank_mask:0xf
	s_nop 1
	v_add_f32_dpp v65, v65, v65 row_half_mirror row_mask:0xf bank_mask:0xf
	v_mov_b32_e32 v75, v225
	s_nop 0
	v_add_f32_dpp v65, v65, v65 row_mirror row_mask:0xf bank_mask:0xf
	v_mov_b32_e32 v68, v65
	v_mul_f32_e32 v76, v18, v75
	v_mul_f32_e32 v76, v42, v76
	v_mul_f32_e32 v42, v17, v75
	v_mul_f32_e32 v77, v39, v42
	s_waitcnt lgkmcnt(0)
	v_permlane16_swap_b32_e32 v65, v68
	v_add_f32_e32 v65, v65, v68
	v_fmamk_f32 v65, v65, 0x3c000000, v204
	v_mul_f32_e32 v39, v26, v75
	v_mul_f32_e32 v39, v61, v39
	v_mul_f32_e32 v68, v41, v41
	v_fmac_f32_e32 v68, v45, v45
	v_mul_f32_e32 v61, v21, v21
	v_fmac_f32_e32 v61, v23, v23
	v_add_f32_e32 v61, v61, v68
	s_nop 1
	v_add_f32_dpp v61, v61, v61 quad_perm:[1,0,3,2] row_mask:0xf bank_mask:0xf
	v_mul_f32_e32 v42, v25, v75
	v_mul_f32_e32 v42, v57, v42
	v_add_f32_dpp v57, v61, v61 quad_perm:[2,3,0,1] row_mask:0xf bank_mask:0xf
	s_nop 1
	v_add_f32_dpp v57, v57, v57 row_half_mirror row_mask:0xf bank_mask:0xf
	v_rsq_f32_e32 v65, v65
	s_nop 0
	v_add_f32_dpp v57, v57, v57 row_mirror row_mask:0xf bank_mask:0xf
	v_mov_b32_e32 v61, v57
	v_mul_f32_e32 v68, v18, v65
	v_mul_f32_e32 v33, v33, v68
	v_mul_f32_e32 v68, v17, v65
	v_mul_f32_e32 v31, v31, v68
	s_waitcnt lgkmcnt(0)
	v_permlane16_swap_b32_e32 v57, v61
	v_add_f32_e32 v57, v57, v61
	v_fmamk_f32 v57, v57, 0x3c000000, v204
	v_mul_f32_e32 v68, v26, v65
	v_mul_f32_e32 v53, v53, v68
	v_mul_f32_e32 v65, v25, v65
	v_mul_f32_e32 v48, v48, v65
	v_mul_f32_e32 v68, v12, v12
	v_mul_f32_e32 v75, v34, v34
	v_fmac_f32_e32 v68, v14, v14
	v_fmac_f32_e32 v75, v38, v38
	v_add_f32_e32 v68, v68, v75
	s_nop 1
	v_add_f32_dpp v68, v68, v68 quad_perm:[1,0,3,2] row_mask:0xf bank_mask:0xf
	s_nop 1
	v_add_f32_dpp v65, v68, v68 quad_perm:[2,3,0,1] row_mask:0xf bank_mask:0xf
	s_nop 1
	v_add_f32_dpp v65, v65, v65 row_half_mirror row_mask:0xf bank_mask:0xf
	v_rsq_f32_e32 v57, v57
	s_nop 0
	v_add_f32_dpp v65, v65, v65 row_mirror row_mask:0xf bank_mask:0xf
	v_mov_b32_e32 v68, v65
	v_mul_f32_e32 v61, v18, v57
	v_mul_f32_e32 v23, v23, v61
	v_mul_f32_e32 v61, v17, v57
	v_mul_f32_e32 v21, v21, v61
	s_waitcnt lgkmcnt(0)
	v_permlane16_swap_b32_e32 v65, v68
	v_add_f32_e32 v65, v65, v68
	v_fmamk_f32 v65, v65, 0x3c000000, v204
	v_mul_f32_e32 v61, v26, v57
	v_mul_f32_e32 v45, v45, v61
	v_mul_f32_e32 v57, v25, v57
	v_mul_f32_e32 v41, v41, v57
	v_mul_f32_e32 v68, v10, v10
	v_mul_f32_e32 v75, v24, v24
	v_fmac_f32_e32 v68, v9, v9
	v_fmac_f32_e32 v75, v30, v30
	v_add_f32_e32 v68, v68, v75
	s_nop 1
	v_add_f32_dpp v68, v68, v68 quad_perm:[1,0,3,2] row_mask:0xf bank_mask:0xf
	s_nop 1
	v_add_f32_dpp v57, v68, v68 quad_perm:[2,3,0,1] row_mask:0xf bank_mask:0xf
	s_nop 1
	v_add_f32_dpp v57, v57, v57 row_half_mirror row_mask:0xf bank_mask:0xf
	v_rsq_f32_e32 v61, v65
	s_nop 0
	v_add_f32_dpp v57, v57, v57 row_mirror row_mask:0xf bank_mask:0xf
	v_mov_b32_e32 v68, v57
	v_mul_f32_e32 v65, v18, v61
	v_mul_f32_e32 v14, v14, v65
	v_mul_f32_e32 v65, v17, v61
	v_mul_f32_e32 v12, v12, v65
	s_waitcnt lgkmcnt(0)
	v_permlane16_swap_b32_e32 v57, v68
	v_add_f32_e32 v57, v57, v68
	v_fmamk_f32 v57, v57, 0x3c000000, v204
	v_mul_f32_e32 v65, v26, v61
	v_mul_f32_e32 v38, v38, v65
	v_mul_f32_e32 v61, v25, v61
	v_mul_f32_e32 v34, v34, v61
	v_mul_f32_e32 v68, v7, v7
	v_mul_f32_e32 v75, v19, v19
	v_fmac_f32_e32 v68, v8, v8
	v_fmac_f32_e32 v75, v16, v16
	v_add_f32_e32 v68, v68, v75
	s_nop 1
	v_add_f32_dpp v68, v68, v68 quad_perm:[1,0,3,2] row_mask:0xf bank_mask:0xf
	s_nop 1
	v_add_f32_dpp v61, v68, v68 quad_perm:[2,3,0,1] row_mask:0xf bank_mask:0xf
	s_nop 1
	v_add_f32_dpp v61, v61, v61 row_half_mirror row_mask:0xf bank_mask:0xf
	v_rsq_f32_e32 v57, v57
	s_nop 0
	v_add_f32_dpp v61, v61, v61 row_mirror row_mask:0xf bank_mask:0xf
	v_mov_b32_e32 v65, v61
	v_mul_f32_e32 v68, v18, v57
	v_mul_f32_e32 v68, v9, v68
	v_mul_f32_e32 v9, v17, v57
	v_mul_f32_e32 v10, v10, v9
	s_waitcnt lgkmcnt(0)
	v_permlane16_swap_b32_e32 v61, v65
	v_add_f32_e32 v9, v61, v65
	v_fmamk_f32 v9, v9, 0x3c000000, v204
	v_mul_f32_e32 v65, v26, v57
	v_mul_f32_e32 v65, v30, v65
	v_mul_f32_e32 v30, v25, v57
	v_mul_f32_e32 v79, v24, v30
	v_mul_f32_e32 v61, v6, v6
	v_fmac_f32_e32 v61, v5, v5
	v_mul_f32_e32 v75, v15, v15
	v_fmac_f32_e32 v75, v13, v13
	v_add_f32_e32 v61, v61, v75
	s_nop 1
	v_add_f32_dpp v57, v61, v61 quad_perm:[1,0,3,2] row_mask:0xf bank_mask:0xf
	s_nop 1
	v_add_f32_dpp v24, v57, v57 quad_perm:[2,3,0,1] row_mask:0xf bank_mask:0xf
	s_nop 1
	v_add_f32_dpp v24, v24, v24 row_half_mirror row_mask:0xf bank_mask:0xf
	s_nop 1
	v_add_f32_dpp v24, v24, v24 row_mirror row_mask:0xf bank_mask:0xf
	v_mov_b32_e32 v30, v24
	v_rsq_f32_e32 v9, v9
	s_nop 0
	v_mul_f32_e32 v57, v18, v9
	v_mul_f32_e32 v57, v8, v57
	s_waitcnt lgkmcnt(0)
	v_permlane16_swap_b32_e32 v24, v30
	v_add_f32_e32 v8, v24, v30
	v_fmamk_f32 v8, v8, 0x3c000000, v204
	v_add3_u32 v78, s10, v4, v3
	v_cvt_pk_bf16_f32 v3, v27, s0
	ds_write_b16 v78, v3
	v_cvt_pk_bf16_f32 v3, v28, s0
	ds_write_b16 v78, v3 offset:64
	v_cvt_pk_bf16_f32 v3, v35, s0
	ds_write_b16 v78, v3 offset:128
	v_cvt_pk_bf16_f32 v3, v36, s0
	ds_write_b16 v78, v3 offset:192
	v_cvt_pk_bf16_f32 v3, v43, s0
	ds_write_b16 v78, v3 offset:256
	v_cvt_pk_bf16_f32 v3, v44, s0
	ds_write_b16 v78, v3 offset:320
	v_cvt_pk_bf16_f32 v3, v51, s0
	ds_write_b16 v78, v3 offset:384
	v_cvt_pk_bf16_f32 v3, v52, s0
	ds_write_b16 v78, v3 offset:448
	v_cvt_pk_bf16_f32 v3, v59, s0
	ds_write_b16 v78, v3 offset:1024
	v_cvt_pk_bf16_f32 v3, v60, s0
	ds_write_b16 v78, v3 offset:1088
	v_cvt_pk_bf16_f32 v3, v66, s0
	ds_write_b16 v78, v3 offset:1152
	v_cvt_pk_bf16_f32 v3, v67, s0
	ds_write_b16 v78, v3 offset:1216
	v_cvt_pk_bf16_f32 v3, v70, s0
	ds_write_b16 v78, v3 offset:1280
	v_cvt_pk_bf16_f32 v3, v71, s0
	ds_write_b16 v78, v3 offset:1344
	v_cvt_pk_bf16_f32 v3, v73, s0
	ds_write_b16 v78, v3 offset:1408
	v_cvt_pk_bf16_f32 v3, v74, s0
	ds_write_b16 v78, v3 offset:1472
	v_cvt_pk_bf16_f32 v3, v69, s0
	ds_write_b16 v78, v3 offset:2048
	v_cvt_pk_bf16_f32 v3, v72, s0
	v_mul_f32_e32 v30, v17, v9
	ds_write_b16 v78, v3 offset:2112
	v_cvt_pk_bf16_f32 v3, v76, s0
	v_mul_f32_e32 v7, v7, v30
	v_mul_f32_e32 v30, v26, v9
	v_mul_f32_e32 v9, v25, v9
	ds_write_b16 v78, v3 offset:2176
	v_cvt_pk_bf16_f32 v3, v77, s0
	v_mul_f32_e32 v75, v19, v9
	ds_write_b16 v78, v3 offset:2240
	v_cvt_pk_bf16_f32 v3, v33, s0
	ds_write_b16 v78, v3 offset:2304
	v_cvt_pk_bf16_f32 v3, v31, s0
	ds_write_b16 v78, v3 offset:2368
	v_cvt_pk_bf16_f32 v3, v23, s0
	v_mul_f32_e32 v16, v16, v30
	ds_write_b16 v78, v3 offset:2432
	v_cvt_pk_bf16_f32 v3, v21, s0
	ds_write_b16 v78, v3 offset:2496
	v_cvt_pk_bf16_f32 v3, v14, s0
	ds_write_b16 v78, v3 offset:3072
	v_cvt_pk_bf16_f32 v3, v12, s0
	ds_write_b16 v78, v3 offset:3136
	v_cvt_pk_bf16_f32 v3, v68, s0
	v_rsq_f32_e32 v8, v8
	ds_write_b16 v78, v3 offset:3200
	v_cvt_pk_bf16_f32 v3, v10, s0
	v_mul_f32_e32 v9, v18, v8
	ds_write_b16 v78, v3 offset:3264
	v_cvt_pk_bf16_f32 v3, v57, s0
	v_mul_f32_e32 v18, v5, v9
	v_mul_f32_e32 v5, v17, v8
	ds_write_b16 v78, v3 offset:3328
	v_cvt_pk_bf16_f32 v3, v7, s0
	v_mul_f32_e32 v6, v6, v5
	ds_write_b16 v78, v3 offset:3392
	v_cvt_pk_bf16_f32 v3, v18, s0
	v_mul_f32_e32 v5, v26, v8
	s_add_u32 s4, s8, s64
	ds_write_b16 v78, v3 offset:3456
	v_cvt_pk_bf16_f32 v3, v6, s0
	v_mul_f32_e32 v17, v13, v5
	v_mul_f32_e32 v5, v25, v8
	s_addc_u32 s5, s9, s65
	ds_write_b16 v78, v3 offset:3520
	v_mul_f32_e32 v61, v15, v5
	v_lshl_add_u64 v[4:5], s[4:5], 0, v[188:189]
	s_mov_b64 s[4:5], 0x18800000
	v_lshl_add_u32 v80, v1, 7, v2
	s_waitcnt lgkmcnt(0)
	v_lshl_add_u64 v[8:9], v[4:5], 0, s[4:5]
	ds_read_b128 v[4:7], v80
	v_or_b32_e32 v3, 8, v1
	v_lshlrev_b32_e32 v12, 11, v1
	v_mov_b32_e32 v13, v146
	v_lshl_add_u32 v10, v3, 7, v2
	v_lshl_add_u64 v[18:19], v[8:9], 0, v[12:13]
	ds_read_b128 v[12:15], v10
	s_waitcnt lgkmcnt(1)
	global_store_dwordx4 v[18:19], v[4:7], off
	s_mov_b64 s[6:7], 0
	s_nop 0
	v_lshlrev_b32_e32 v4, 11, v3
	v_mov_b32_e32 v5, v146
	v_or_b32_e32 v3, 16, v1
	v_lshl_add_u64 v[24:25], v[8:9], 0, v[4:5]
	v_lshl_add_u32 v21, v3, 7, v2
	v_or_b32_e32 v1, 24, v1
	ds_read_b128 v[4:7], v21
	s_waitcnt lgkmcnt(1)
	global_store_dwordx4 v[24:25], v[12:15], off
	v_lshl_add_u32 v23, v1, 7, v2
	v_lshlrev_b32_e32 v2, 11, v1
	v_lshlrev_b32_e32 v12, 11, v3
	v_mov_b32_e32 v13, v146
	v_lshl_add_u64 v[26:27], v[8:9], 0, v[12:13]
	ds_read_b128 v[12:15], v23
	v_mov_b32_e32 v3, v146
	v_lshl_add_u64 v[30:31], v[8:9], 0, v[2:3]
	s_waitcnt lgkmcnt(1)
	global_store_dwordx4 v[26:27], v[4:7], off
	v_cvt_pk_bf16_f32 v1, v11, s0
	s_waitcnt lgkmcnt(0)
	global_store_dwordx4 v[30:31], v[12:15], off
	ds_write_b16 v78, v1
	v_cvt_pk_bf16_f32 v1, v20, s0
	ds_write_b16 v78, v1 offset:64
	v_cvt_pk_bf16_f32 v1, v22, s0
	ds_write_b16 v78, v1 offset:128
	v_cvt_pk_bf16_f32 v1, v29, s0
	ds_write_b16 v78, v1 offset:192
	v_cvt_pk_bf16_f32 v1, v32, s0
	ds_write_b16 v78, v1 offset:256
	v_cvt_pk_bf16_f32 v1, v37, s0
	ds_write_b16 v78, v1 offset:320
	v_cvt_pk_bf16_f32 v1, v40, s0
	ds_write_b16 v78, v1 offset:384
	v_cvt_pk_bf16_f32 v1, v46, s0
	ds_write_b16 v78, v1 offset:448
	v_cvt_pk_bf16_f32 v1, v49, s0
	ds_write_b16 v78, v1 offset:1024
	v_cvt_pk_bf16_f32 v1, v55, s0
	ds_write_b16 v78, v1 offset:1088
	v_cvt_pk_bf16_f32 v1, v58, s0
	ds_write_b16 v78, v1 offset:1152
	v_cvt_pk_bf16_f32 v1, v63, s0
	ds_write_b16 v78, v1 offset:1216
	v_cvt_pk_bf16_f32 v1, v62, s0
	ds_write_b16 v78, v1 offset:1280
	v_cvt_pk_bf16_f32 v1, v64, s0
	ds_write_b16 v78, v1 offset:1344
	v_cvt_pk_bf16_f32 v1, v54, s0
	ds_write_b16 v78, v1 offset:1408
	v_cvt_pk_bf16_f32 v1, v56, s0
	ds_write_b16 v78, v1 offset:1472
	v_cvt_pk_bf16_f32 v1, v47, s0
	ds_write_b16 v78, v1 offset:2048
	v_cvt_pk_bf16_f32 v1, v50, s0
	ds_write_b16 v78, v1 offset:2112
	v_cvt_pk_bf16_f32 v1, v39, s0
	ds_write_b16 v78, v1 offset:2176
	v_cvt_pk_bf16_f32 v1, v42, s0
	ds_write_b16 v78, v1 offset:2240
	v_cvt_pk_bf16_f32 v1, v53, s0
	ds_write_b16 v78, v1 offset:2304
	v_cvt_pk_bf16_f32 v1, v48, s0
	ds_write_b16 v78, v1 offset:2368
	v_cvt_pk_bf16_f32 v1, v45, s0
	ds_write_b16 v78, v1 offset:2432
	v_cvt_pk_bf16_f32 v1, v41, s0
	ds_write_b16 v78, v1 offset:2496
	v_cvt_pk_bf16_f32 v1, v38, s0
	ds_write_b16 v78, v1 offset:3072
	v_cvt_pk_bf16_f32 v1, v34, s0
	ds_write_b16 v78, v1 offset:3136
	v_cvt_pk_bf16_f32 v1, v65, s0
	ds_write_b16 v78, v1 offset:3200
	v_cvt_pk_bf16_f32 v1, v79, s0
	ds_write_b16 v78, v1 offset:3264
	v_cvt_pk_bf16_f32 v1, v16, s0
	ds_write_b16 v78, v1 offset:3328
	v_cvt_pk_bf16_f32 v1, v75, s0
	ds_write_b16 v78, v1 offset:3392
	v_cvt_pk_bf16_f32 v1, v17, s0
	ds_write_b16 v78, v1 offset:3456
	v_cvt_pk_bf16_f32 v1, v61, s0
	ds_write_b16 v78, v1 offset:3520
	s_waitcnt lgkmcnt(0)
	ds_read_b128 v[2:5], v80
	ds_read_b128 v[6:9], v10
	ds_read_b128 v[10:13], v21
	ds_read_b128 v[14:17], v23
	s_waitcnt lgkmcnt(3)
	global_store_dwordx4 v[18:19], v[2:5], off offset:128
	s_waitcnt lgkmcnt(2)
	global_store_dwordx4 v[24:25], v[6:9], off offset:128
	s_waitcnt lgkmcnt(1)
	global_store_dwordx4 v[26:27], v[10:13], off offset:128
	s_waitcnt lgkmcnt(0)
	global_store_dwordx4 v[30:31], v[14:17], off offset:128
	s_barrier
